# hosted weight conversion: second item's loads issued before the wait for the first item's data (both HBM round trips overlap); on top of j2
# speedup vs baseline: 1.0030x; 1.0030x over previous
; __device__ __forceinline__ void cv_load(f32x4 (&v)[16], const CvItem& c) {
; #pragma unroll
;     for (int i = 0; i < 16; ++i) v[i] = *(const f32x4*)((const char*)uni(c.src + (size_t)(4 * i) * c.ldw) + c.voff);
; }
.LBB0_913:
	s_cmp_lg_u32 s47, 11
	s_cselect_b64 s[6:7], -1, 0
	s_lshl_b32 s33, s4, 4
	s_add_u32 s4, s2, s33
	s_addc_u32 s5, s3, 0
	s_add_u32 s12, s4, s33
	s_addc_u32 s13, s5, 0
	s_add_u32 s14, s12, s33
	s_addc_u32 s15, s13, 0
	s_add_u32 s16, s14, s33
	s_addc_u32 s17, s15, 0
	s_add_u32 s20, s16, s33
	s_addc_u32 s21, s17, 0
	s_add_u32 s22, s20, s33
	s_addc_u32 s23, s21, 0
	s_add_u32 s34, s22, s33
	s_addc_u32 s35, s23, 0
	s_add_u32 s36, s34, s33
	s_addc_u32 s37, s35, 0
	s_add_u32 s38, s36, s33
	s_addc_u32 s39, s37, 0
	s_add_u32 s74, s38, s33
	s_addc_u32 s75, s39, 0
	s_add_u32 s76, s74, s33
	s_addc_u32 s77, s75, 0
	s_add_u32 s78, s76, s33
	s_addc_u32 s79, s77, 0
	s_add_u32 s80, s78, s33
	s_addc_u32 s81, s79, 0
	s_add_u32 s82, s80, s33
	s_addc_u32 s83, s81, 0
	s_add_u32 s84, s82, s33
	s_addc_u32 s85, s83, 0
	global_load_dwordx4 v[90:93], v0, s[2:3]
	global_load_dwordx4 v[114:117], v0, s[4:5]
	global_load_dwordx4 v[126:129], v0, s[12:13]
	global_load_dwordx4 v[102:105], v0, s[14:15]
	global_load_dwordx4 v[78:81], v0, s[16:17]
	global_load_dwordx4 v[106:109], v0, s[20:21]
	global_load_dwordx4 v[122:125], v0, s[22:23]
	global_load_dwordx4 v[94:97], v0, s[34:35]
	global_load_dwordx4 v[70:73], v0, s[36:37]
	global_load_dwordx4 v[98:101], v0, s[38:39]
	global_load_dwordx4 v[118:121], v0, s[74:75]
	global_load_dwordx4 v[82:85], v0, s[76:77]
	global_load_dwordx4 v[66:69], v0, s[78:79]
	global_load_dwordx4 v[86:89], v0, s[80:81]
	global_load_dwordx4 v[110:113], v0, s[82:83]
	global_load_dwordx4 v[74:77], v0, s[84:85]
	s_cmp_eq_u32 s47, 11
	s_cbranch_scc1 .Lmy_cv_single0
	s_mov_b64 s[2:3], s[8:9]
	s_mov_b64 s[4:5], s[10:11]
	s_mov_b32 s16, s18
	s_mov_b32 s17, s19
	s_mov_b32 s33, 0x8000
	s_add_i32 s2, s47, 1
	v_readlane_b32 s4, v254, 26
	s_mul_i32 s20, s2, s4
	v_readlane_b32 s2, v254, 22
	s_add_i32 s20, s20, s2
	v_readlane_b32 s3, v254, 23
	s_mul_hi_i32 s2, s20, 0x2fa0be83
	s_lshr_b32 s3, s2, 31
	s_ashr_i32 s16, s2, 11
	s_add_i32 s16, s16, s3
	s_mul_i32 s2, s16, 0x2b00
	s_sub_i32 s2, s20, s2
	s_mul_i32 s3, s2, 0x2fa1
	s_lshr_b32 s4, s3, 31
	s_ashr_i32 s17, s3, 23
	s_add_i32 s17, s17, s4
	s_mul_i32 s3, s17, 0x2b0
	s_sub_i32 s21, s2, s3
	v_readlane_b32 s5, v254, 27
	s_cmpk_gt_i32 s20, 0x55ff
	s_mov_b64 s[14:15], -1
	v_mbcnt_lo_u32_b32 v2, -1, 0
	v_mbcnt_hi_u32_b32 v2, -1, v2
	s_cbranch_scc0 .LBB0_916
	s_and_b32 s2, 0xffff, s21
	s_lshl_b32 s3, s2, 6
	s_and_b32 s12, s3, 0x3c0
	s_lshl_b32 s4, s2, 2
	s_load_dwordx2 s[2:3], s[24:25], 0xc8
	s_and_b32 s13, s4, 0xfc0
	s_add_i32 s4, s67, s17
	s_mov_b32 s5, s87
	s_mul_i32 s4, s4, 0x2b0000
	s_lshl_b64 s[4:5], s[4:5], 2
	s_waitcnt lgkmcnt(0)
	s_add_u32 s4, s2, s4
	s_addc_u32 s5, s3, s5
	s_lshl_b32 s2, s17, 10
	s_or_b32 s2, s12, s2
	s_mulk_i32 s2, 0xb00
	s_add_u32 s2, s68, s2
	s_addc_u32 s3, s69, 0
	s_add_u32 s2, s2, s13
	s_addc_u32 s3, s3, 0
	s_lshl_b32 s13, s13, 12
	s_add_u32 s4, s4, s13
	s_addc_u32 s5, s5, 0
	s_lshl_b32 s12, s12, 2
	s_add_u32 s12, s4, s12
	v_lshlrev_b32_e32 v3, 4, v2
	s_addc_u32 s13, s5, 0
	v_lshlrev_b32_e32 v0, 8, v2
	v_and_b32_e32 v3, 0xf0, v3
	s_movk_i32 s4, 0xf000
	v_and_or_b32 v0, v0, s4, v3
	s_add_u32 s4, s2, 0x16000
	s_addc_u32 s5, s3, 0
	s_mov_b64 s[14:15], 0

; __device__ __forceinline__ void cv_load(f32x4 (&v)[16], const CvItem& c) {
; #pragma unroll
;     for (int i = 0; i < 16; ++i) v[i] = *(const f32x4*)((const char*)uni(c.src + (size_t)(4 * i) * c.ldw) + c.voff);
; }
.LBB0_919:
	s_lshl_b32 s14, s14, 4
	global_load_dwordx4 v[2:5], v0, s[12:13]
	s_add_u32 s12, s12, s14
	s_addc_u32 s13, s13, 0
	global_load_dwordx4 v[14:17], v0, s[12:13]
	s_add_u32 s12, s12, s14
	s_addc_u32 s13, s13, 0
	global_load_dwordx4 v[6:9], v0, s[12:13]
	s_add_u32 s12, s12, s14
	s_addc_u32 s13, s13, 0
	global_load_dwordx4 v[18:21], v0, s[12:13]
	s_add_u32 s12, s12, s14
	s_addc_u32 s13, s13, 0
	global_load_dwordx4 v[10:13], v0, s[12:13]
	s_add_u32 s12, s12, s14
	s_addc_u32 s13, s13, 0
	global_load_dwordx4 v[22:25], v0, s[12:13]
	s_add_u32 s12, s12, s14
	s_addc_u32 s13, s13, 0
	global_load_dwordx4 v[26:29], v0, s[12:13]
	s_add_u32 s12, s12, s14
	s_addc_u32 s13, s13, 0
	global_load_dwordx4 v[34:37], v0, s[12:13]
	s_add_u32 s12, s12, s14
	s_addc_u32 s13, s13, 0
	global_load_dwordx4 v[30:33], v0, s[12:13]
	s_add_u32 s12, s12, s14
	s_addc_u32 s13, s13, 0
	global_load_dwordx4 v[38:41], v0, s[12:13]
	s_add_u32 s12, s12, s14
	s_addc_u32 s13, s13, 0
	global_load_dwordx4 v[42:45], v0, s[12:13]
	s_add_u32 s12, s12, s14
	s_addc_u32 s13, s13, 0
	global_load_dwordx4 v[50:53], v0, s[12:13]
	s_add_u32 s12, s12, s14
	s_addc_u32 s13, s13, 0
	global_load_dwordx4 v[46:49], v0, s[12:13]
	s_add_u32 s12, s12, s14
	s_addc_u32 s13, s13, 0
	global_load_dwordx4 v[54:57], v0, s[12:13]
	s_add_u32 s12, s12, s14
	s_addc_u32 s13, s13, 0
	global_load_dwordx4 v[58:61], v0, s[12:13]
	s_add_u32 s12, s12, s14
	s_addc_u32 s13, s13, 0
	global_load_dwordx4 v[62:65], v0, s[12:13]
	s_waitcnt vmcnt(16)
	s_branch .LBB0_920
.Lmy_cv_single0:
	s_waitcnt vmcnt(0)
	v_mov_b64_e32 v[62:63], v[74:75]
	v_mov_b64_e32 v[58:59], v[110:111]
	v_mov_b64_e32 v[54:55], v[86:87]
	v_mov_b64_e32 v[46:47], v[66:67]
	v_mov_b64_e32 v[50:51], v[82:83]
	v_mov_b64_e32 v[42:43], v[118:119]
	v_mov_b64_e32 v[38:39], v[98:99]
	v_mov_b64_e32 v[30:31], v[70:71]
	v_mov_b64_e32 v[34:35], v[94:95]
	v_mov_b64_e32 v[26:27], v[122:123]
	v_mov_b64_e32 v[22:23], v[106:107]
	v_mov_b64_e32 v[10:11], v[78:79]
	v_mov_b64_e32 v[18:19], v[102:103]
	v_mov_b64_e32 v[6:7], v[126:127]
	v_mov_b64_e32 v[2:3], v[90:91]
	v_mov_b64_e32 v[14:15], v[114:115]
	v_mov_b64_e32 v[64:65], v[76:77]
	v_mov_b64_e32 v[60:61], v[112:113]
	v_mov_b64_e32 v[56:57], v[88:89]
	v_mov_b64_e32 v[48:49], v[68:69]
	v_mov_b64_e32 v[52:53], v[84:85]
	v_mov_b64_e32 v[44:45], v[120:121]
	v_mov_b64_e32 v[40:41], v[100:101]
	v_mov_b64_e32 v[32:33], v[72:73]
	v_mov_b64_e32 v[36:37], v[96:97]
	v_mov_b64_e32 v[28:29], v[124:125]
	v_mov_b64_e32 v[24:25], v[108:109]
	v_mov_b64_e32 v[12:13], v[80:81]
	v_mov_b64_e32 v[20:21], v[104:105]
	v_mov_b64_e32 v[8:9], v[128:129]
	s_mov_b64 s[2:3], s[8:9]
	s_mov_b64 s[4:5], s[10:11]
	s_mov_b32 s16, s18
	s_mov_b32 s17, s19
	v_mov_b64_e32 v[4:5], v[92:93]
	v_mov_b64_e32 v[16:17], v[116:117]
	s_mov_b32 s33, 0x8000

; __device__ __forceinline__ void cv_load(f32x4 (&v)[16], const CvItem& c) {
; #pragma unroll
;     for (int i = 0; i < 16; ++i) v[i] = *(const f32x4*)((const char*)uni(c.src + (size_t)(4 * i) * c.ldw) + c.voff);
; }
.LBB0_929:
	s_cmp_lg_u32 s47, 11
	s_cselect_b64 s[6:7], -1, 0
	s_lshl_b32 s33, s4, 4
	s_add_u32 s4, s2, s33
	s_addc_u32 s5, s3, 0
	s_add_u32 s12, s4, s33
	s_addc_u32 s13, s5, 0
	s_add_u32 s14, s12, s33
	s_addc_u32 s15, s13, 0
	s_add_u32 s16, s14, s33
	s_addc_u32 s17, s15, 0
	s_add_u32 s20, s16, s33
	s_addc_u32 s21, s17, 0
	s_add_u32 s22, s20, s33
	s_addc_u32 s23, s21, 0
	s_add_u32 s34, s22, s33
	s_addc_u32 s35, s23, 0
	s_add_u32 s36, s34, s33
	s_addc_u32 s37, s35, 0
	s_add_u32 s38, s36, s33
	s_addc_u32 s39, s37, 0
	s_add_u32 s74, s38, s33
	s_addc_u32 s75, s39, 0
	s_add_u32 s76, s74, s33
	s_addc_u32 s77, s75, 0
	s_add_u32 s78, s76, s33
	s_addc_u32 s79, s77, 0
	s_add_u32 s80, s78, s33
	s_addc_u32 s81, s79, 0
	s_add_u32 s82, s80, s33
	s_addc_u32 s83, s81, 0
	s_add_u32 s84, s82, s33
	s_addc_u32 s85, s83, 0
	global_load_dwordx4 v[90:93], v0, s[2:3]
	global_load_dwordx4 v[114:117], v0, s[4:5]
	global_load_dwordx4 v[126:129], v0, s[12:13]
	global_load_dwordx4 v[102:105], v0, s[14:15]
	global_load_dwordx4 v[78:81], v0, s[16:17]
	global_load_dwordx4 v[106:109], v0, s[20:21]
	global_load_dwordx4 v[122:125], v0, s[22:23]
	global_load_dwordx4 v[94:97], v0, s[34:35]
	global_load_dwordx4 v[70:73], v0, s[36:37]
	global_load_dwordx4 v[98:101], v0, s[38:39]
	global_load_dwordx4 v[118:121], v0, s[74:75]
	global_load_dwordx4 v[82:85], v0, s[76:77]
	global_load_dwordx4 v[66:69], v0, s[78:79]
	global_load_dwordx4 v[86:89], v0, s[80:81]
	global_load_dwordx4 v[110:113], v0, s[82:83]
	global_load_dwordx4 v[74:77], v0, s[84:85]
	s_cmp_eq_u32 s47, 11
	s_cbranch_scc1 .Lmy_cv_single1
	s_mov_b64 s[2:3], s[8:9]
	s_mov_b64 s[4:5], s[10:11]
	s_mov_b32 s16, s18
	s_mov_b32 s17, s19
	s_add_i32 s2, s47, 1
	v_readlane_b32 s4, v254, 26
	s_mul_i32 s20, s2, s4
	v_readlane_b32 s2, v254, 22
	s_add_i32 s20, s20, s2
	v_readlane_b32 s3, v254, 23
	s_mul_hi_i32 s2, s20, 0x2fa0be83
	s_lshr_b32 s3, s2, 31
	s_ashr_i32 s16, s2, 11
	s_add_i32 s16, s16, s3
	s_mul_i32 s2, s16, 0x2b00
	s_sub_i32 s2, s20, s2
	s_mul_i32 s3, s2, 0x2fa1
	s_lshr_b32 s4, s3, 31
	s_ashr_i32 s17, s3, 23
	s_add_i32 s17, s17, s4
	s_mul_i32 s3, s17, 0x2b0
	s_sub_i32 s21, s2, s3
	v_readlane_b32 s5, v254, 27
	s_cmpk_gt_i32 s20, 0x55ff
	s_mov_b64 s[14:15], -1
	v_mbcnt_lo_u32_b32 v2, -1, 0
	v_mbcnt_hi_u32_b32 v2, -1, v2
	s_cbranch_scc0 .LBB0_932
	s_and_b32 s2, 0xffff, s21
	s_lshl_b32 s3, s2, 6
	s_and_b32 s12, s3, 0x3c0
	s_lshl_b32 s4, s2, 2
	s_load_dwordx2 s[2:3], s[24:25], 0xc8
	s_and_b32 s13, s4, 0xfc0
	s_add_i32 s4, s67, s17
	s_mov_b32 s5, s87
	s_mul_i32 s4, s4, 0x2b0000
	s_lshl_b64 s[4:5], s[4:5], 2
	s_waitcnt lgkmcnt(0)
	s_add_u32 s4, s2, s4
	s_addc_u32 s5, s3, s5
	s_lshl_b32 s2, s17, 10
	s_or_b32 s2, s12, s2
	s_mulk_i32 s2, 0xb00
	s_add_u32 s2, s68, s2
	s_addc_u32 s3, s69, 0
	s_add_u32 s2, s2, s13
	s_addc_u32 s3, s3, 0
	s_lshl_b32 s13, s13, 12
	s_add_u32 s4, s4, s13
	s_addc_u32 s5, s5, 0
	s_lshl_b32 s12, s12, 2
	s_add_u32 s12, s4, s12
	v_lshlrev_b32_e32 v3, 4, v2
	s_addc_u32 s13, s5, 0
	v_lshlrev_b32_e32 v0, 8, v2
	v_and_b32_e32 v3, 0xf0, v3
	s_movk_i32 s4, 0xf000
	v_and_or_b32 v0, v0, s4, v3
	s_add_u32 s4, s2, 0x16000
	s_addc_u32 s5, s3, 0
	s_mov_b64 s[14:15], 0

; __device__ __forceinline__ void cv_load(f32x4 (&v)[16], const CvItem& c) {
; #pragma unroll
;     for (int i = 0; i < 16; ++i) v[i] = *(const f32x4*)((const char*)uni(c.src + (size_t)(4 * i) * c.ldw) + c.voff);
; }
.LBB0_935:
	s_lshl_b32 s14, s14, 4
	global_load_dwordx4 v[2:5], v0, s[12:13]
	s_add_u32 s12, s12, s14
	s_addc_u32 s13, s13, 0
	global_load_dwordx4 v[6:9], v0, s[12:13]
	s_add_u32 s12, s12, s14
	s_addc_u32 s13, s13, 0
	global_load_dwordx4 v[10:13], v0, s[12:13]
	s_add_u32 s12, s12, s14
	s_addc_u32 s13, s13, 0
	global_load_dwordx4 v[18:21], v0, s[12:13]
	s_add_u32 s12, s12, s14
	s_addc_u32 s13, s13, 0
	global_load_dwordx4 v[14:17], v0, s[12:13]
	s_add_u32 s12, s12, s14
	s_addc_u32 s13, s13, 0
	global_load_dwordx4 v[22:25], v0, s[12:13]
	s_add_u32 s12, s12, s14
	s_addc_u32 s13, s13, 0
	global_load_dwordx4 v[26:29], v0, s[12:13]
	s_add_u32 s12, s12, s14
	s_addc_u32 s13, s13, 0
	global_load_dwordx4 v[34:37], v0, s[12:13]
	s_add_u32 s12, s12, s14
	s_addc_u32 s13, s13, 0
	global_load_dwordx4 v[30:33], v0, s[12:13]
	s_add_u32 s12, s12, s14
	s_addc_u32 s13, s13, 0
	global_load_dwordx4 v[38:41], v0, s[12:13]
	s_add_u32 s12, s12, s14
	s_addc_u32 s13, s13, 0
	global_load_dwordx4 v[42:45], v0, s[12:13]
	s_add_u32 s12, s12, s14
	s_addc_u32 s13, s13, 0
	global_load_dwordx4 v[50:53], v0, s[12:13]
	s_add_u32 s12, s12, s14
	s_addc_u32 s13, s13, 0
	global_load_dwordx4 v[46:49], v0, s[12:13]
	s_add_u32 s12, s12, s14
	s_addc_u32 s13, s13, 0
	global_load_dwordx4 v[54:57], v0, s[12:13]
	s_add_u32 s12, s12, s14
	s_addc_u32 s13, s13, 0
	global_load_dwordx4 v[58:61], v0, s[12:13]
	s_add_u32 s12, s12, s14
	s_addc_u32 s13, s13, 0
	global_load_dwordx4 v[62:65], v0, s[12:13]
	s_waitcnt vmcnt(16)
	s_branch .LBB0_936
.Lmy_cv_single1:
	s_waitcnt vmcnt(15)
	v_mov_b64_e32 v[2:3], v[90:91]
	s_waitcnt vmcnt(14)
	v_mov_b64_e32 v[6:7], v[114:115]
	s_waitcnt vmcnt(13)
	v_mov_b64_e32 v[10:11], v[126:127]
	s_waitcnt vmcnt(12)
	v_mov_b64_e32 v[18:19], v[102:103]
	s_waitcnt vmcnt(11)
	v_mov_b64_e32 v[14:15], v[78:79]
	s_waitcnt vmcnt(10)
	v_mov_b64_e32 v[22:23], v[106:107]
	s_waitcnt vmcnt(9)
	v_mov_b64_e32 v[26:27], v[122:123]
	s_waitcnt vmcnt(8)
	v_mov_b64_e32 v[34:35], v[94:95]
	s_waitcnt vmcnt(7)
	v_mov_b64_e32 v[30:31], v[70:71]
	s_waitcnt vmcnt(6)
	v_mov_b64_e32 v[38:39], v[98:99]
	s_waitcnt vmcnt(5)
	v_mov_b64_e32 v[42:43], v[118:119]
	s_waitcnt vmcnt(4)
	v_mov_b64_e32 v[50:51], v[82:83]
	s_waitcnt vmcnt(3)
	v_mov_b64_e32 v[46:47], v[66:67]
	s_waitcnt vmcnt(2)
	v_mov_b64_e32 v[54:55], v[86:87]
	s_waitcnt vmcnt(1)
	v_mov_b64_e32 v[58:59], v[110:111]
	s_waitcnt vmcnt(0)
	v_mov_b64_e32 v[62:63], v[74:75]
	s_mov_b64 s[2:3], s[8:9]
	s_mov_b64 s[4:5], s[10:11]
	s_mov_b32 s16, s18
	s_mov_b32 s17, s19
	v_mov_b64_e32 v[4:5], v[92:93]
	v_mov_b64_e32 v[8:9], v[116:117]
	v_mov_b64_e32 v[12:13], v[128:129]
	v_mov_b64_e32 v[20:21], v[104:105]
	v_mov_b64_e32 v[16:17], v[80:81]
	v_mov_b64_e32 v[24:25], v[108:109]
	v_mov_b64_e32 v[28:29], v[124:125]
	v_mov_b64_e32 v[36:37], v[96:97]
	v_mov_b64_e32 v[32:33], v[72:73]
	v_mov_b64_e32 v[40:41], v[100:101]
	v_mov_b64_e32 v[44:45], v[120:121]
	v_mov_b64_e32 v[52:53], v[84:85]
	v_mov_b64_e32 v[48:49], v[68:69]
	v_mov_b64_e32 v[56:57], v[88:89]
	v_mov_b64_e32 v[60:61], v[112:113]
	v_mov_b64_e32 v[64:65], v[76:77]
